# C2 dir loops: ds_read_b128 operands of the S^T and num MFMA chains renamed to free quads and issued together (counted lgkmcnt waits)
# baseline (speedup 1.0000x reference)
.LBB0_1331:
	s_or_b64 exec, exec, s[4:5]
	v_mul_lo_u32 v37, v34, s46
	v_add_u32_e32 v87, 0, v0
	v_add_u32_e32 v18, v87, v37
	v_lshl_add_u32 v42, v34, 2, s45
	ds_read2st64_b32 v[38:39], v42 offset0:4 offset1:10
	ds_read_b128 v[30:33], v18
	ds_read_b128 v[26:29], v18 offset:64
	ds_read_b128 v[22:25], v18 offset:128
	s_waitcnt lgkmcnt(4)
	ds_read_b128 v[18:21], v18 offset:192
	s_waitcnt lgkmcnt(4)
	v_sub_f32_e32 v43, v38, v39
	v_lshlrev_b32_e32 v44, 2, v40
	v_mov_b32_e32 v36, 0
	v_mov_b32_e32 v39, 0
	s_cmp_lt_i32 s7, 0
	v_mad_u32_u24 v35, v86, s46, v87
	v_mov_b32_e32 v38, 0
	v_mov_b32_e32 v50, 0
	s_cbranch_scc1 .LBB0_1333
	ds_read_b128 v[198:201], v35 offset:34816
	ds_read_b128 v[202:205], v35 offset:34880
	ds_read_b128 v[206:209], v35 offset:34944
	ds_read_b128 v[234:237], v35 offset:35008
	v_lshl_add_u32 v38, v44, 2, 0
	v_add_u32_e32 v38, 0x22600, v38
	v_cmp_le_i32_e32 vcc, v44, v34
	s_waitcnt lgkmcnt(3)
	v_mfma_f32_16x16x32_bf16 v[50:53], v[198:201], v[30:33], 0
	s_waitcnt lgkmcnt(2)
	v_mfma_f32_16x16x32_bf16 v[50:53], v[202:205], v[26:29], v[50:53]
	s_waitcnt lgkmcnt(1)
	v_mfma_f32_16x16x32_bf16 v[50:53], v[206:209], v[22:25], v[50:53]
	s_waitcnt lgkmcnt(0)
	v_mfma_f32_16x16x32_bf16 v[50:53], v[234:237], v[18:21], v[50:53]
	ds_read_b128 v[54:57], v38
	s_waitcnt lgkmcnt(0)
	v_add_f32_e32 v38, v43, v54
	v_mul_f32_e32 v38, 0x3fb8aa3b, v38
	v_add_f32_e32 v39, v43, v55
	v_exp_f32_e32 v38, v38
	v_mul_f32_e32 v39, 0x3fb8aa3b, v39
	v_exp_f32_e32 v39, v39
	v_or_b32_e32 v54, 3, v44
	v_mul_f32_e32 v38, v50, v38
	v_cndmask_b32_e32 v45, 0, v38, vcc
	v_cmp_lt_i32_e32 vcc, v44, v34
	v_mul_f32_e32 v39, v51, v39
	v_add_f32_e32 v38, 0, v45
	v_cndmask_b32_e32 v51, 0, v39, vcc
	v_add_f32_e32 v50, v51, v38
	v_add_f32_e32 v38, v43, v56
	v_add_f32_e32 v39, v43, v57
	v_mul_f32_e32 v38, 0x3fb8aa3b, v38
	v_mul_f32_e32 v39, 0x3fb8aa3b, v39
	v_exp_f32_e32 v38, v38
	v_exp_f32_e32 v39, v39
	v_or_b32_e32 v55, 2, v44
	v_cmp_le_i32_e32 vcc, v54, v34
	v_pk_mul_f32 v[38:39], v[52:53], v[38:39]
	s_nop 0
	v_cndmask_b32_e32 v39, 0, v39, vcc
	v_cmp_le_i32_e32 vcc, v55, v34
	s_nop 1
	v_cndmask_b32_e32 v52, 0, v38, vcc
	v_add_f32_e32 v38, v52, v50
	v_add_f32_e32 v50, v39, v38
	v_cvt_pk_bf16_f32 v38, v45, v51
	v_cvt_pk_bf16_f32 v39, v52, v39
.LBB0_1333:
	v_lshlrev_b32_e32 v45, 3, v40
	v_add_u32_e32 v37, s34, v37
	v_add_u32_e32 v45, v37, v45
	ds_write_b64 v45, v[38:39]
	s_cmp_lt_i32 s7, 1
	s_cbranch_scc1 .LBB0_1337
	ds_read_b128 v[198:201], v35 offset:39168
	ds_read_b128 v[202:205], v35 offset:39232
	ds_read_b128 v[206:209], v35 offset:39296
	ds_read_b128 v[234:237], v35 offset:39360
	v_or_b32_e32 v56, 16, v44
	v_or_b32_e32 v51, 17, v44
	v_cmp_le_i32_e32 vcc, v51, v34
	s_waitcnt lgkmcnt(3)
	v_mfma_f32_16x16x32_bf16 v[36:39], v[198:201], v[30:33], 0
	s_waitcnt lgkmcnt(2)
	v_mfma_f32_16x16x32_bf16 v[36:39], v[202:205], v[26:29], v[36:39]
	s_waitcnt lgkmcnt(1)
	v_mfma_f32_16x16x32_bf16 v[36:39], v[206:209], v[22:25], v[36:39]
	s_waitcnt lgkmcnt(0)
	v_mfma_f32_16x16x32_bf16 v[36:39], v[234:237], v[18:21], v[36:39]
	v_lshl_add_u32 v52, v56, 2, 0
	v_add_u32_e32 v52, 0x22600, v52
	ds_read_b128 v[52:55], v52
	s_waitcnt lgkmcnt(0)
	v_add_f32_e32 v52, v43, v52
	v_add_f32_e32 v53, v43, v53
	v_mul_f32_e32 v52, 0x3fb8aa3b, v52
	v_mul_f32_e32 v53, 0x3fb8aa3b, v53
	v_exp_f32_e32 v52, v52
	v_exp_f32_e32 v53, v53
	s_nop 0
	v_pk_mul_f32 v[36:37], v[36:37], v[52:53]
	s_nop 0
	v_cndmask_b32_e32 v51, 0, v37, vcc
	v_cmp_le_i32_e32 vcc, v56, v34
	v_add_f32_e32 v37, v43, v55
	v_mul_f32_e32 v37, 0x3fb8aa3b, v37
	v_cndmask_b32_e32 v52, 0, v36, vcc
	v_add_f32_e32 v36, v50, v52
	v_add_f32_e32 v50, v51, v36
	v_add_f32_e32 v36, v43, v54
	v_mul_f32_e32 v36, 0x3fb8aa3b, v36
	v_exp_f32_e32 v36, v36
	v_exp_f32_e32 v37, v37
	v_or_b32_e32 v53, 19, v44
	v_or_b32_e32 v56, 18, v44
	v_cmp_le_i32_e32 vcc, v53, v34
	v_pk_mul_f32 v[36:37], v[38:39], v[36:37]
	s_nop 0
	v_cndmask_b32_e32 v37, 0, v37, vcc
	v_cmp_le_i32_e32 vcc, v56, v34
	s_nop 1
	v_cndmask_b32_e32 v38, 0, v36, vcc
	v_add_f32_e32 v36, v38, v50
	v_add_f32_e32 v50, v37, v36
	v_cvt_pk_bf16_f32 v36, v52, v51
	v_cvt_pk_bf16_f32 v37, v38, v37
	s_branch .LBB0_1338

.LBB0_1338:
	ds_write_b64 v45, v[36:37] offset:32
	v_mov_b32_e32 v36, 0
	s_cmp_lt_i32 s7, 2
	v_mov_b32_e32 v38, 0
	v_mov_b32_e32 v39, 0
	s_cbranch_scc1 .LBB0_1340
	ds_read_b128 v[198:201], v35 offset:43520
	ds_read_b128 v[202:205], v35 offset:43584
	ds_read_b128 v[206:209], v35 offset:43648
	ds_read_b128 v[234:237], v35 offset:43712
	v_or_b32_e32 v51, 32, v44
	v_lshl_add_u32 v38, v51, 2, 0
	v_add_u32_e32 v38, 0x22600, v38
	v_or_b32_e32 v37, 33, v44
	v_cmp_le_i32_e32 vcc, v37, v34
	s_waitcnt lgkmcnt(3)
	v_mfma_f32_16x16x32_bf16 v[52:55], v[198:201], v[30:33], 0
	s_waitcnt lgkmcnt(2)
	v_mfma_f32_16x16x32_bf16 v[52:55], v[202:205], v[26:29], v[52:55]
	s_waitcnt lgkmcnt(1)
	v_mfma_f32_16x16x32_bf16 v[52:55], v[206:209], v[22:25], v[52:55]
	s_waitcnt lgkmcnt(0)
	v_mfma_f32_16x16x32_bf16 v[52:55], v[234:237], v[18:21], v[52:55]
	ds_read_b128 v[56:59], v38
	s_waitcnt lgkmcnt(0)
	v_add_f32_e32 v38, v43, v56
	v_add_f32_e32 v39, v43, v57
	v_mul_f32_e32 v38, 0x3fb8aa3b, v38
	v_mul_f32_e32 v39, 0x3fb8aa3b, v39
	v_exp_f32_e32 v38, v38
	v_exp_f32_e32 v39, v39
	s_nop 0
	v_pk_mul_f32 v[38:39], v[52:53], v[38:39]
	s_nop 0
	v_cndmask_b32_e32 v37, 0, v39, vcc
	v_cmp_le_i32_e32 vcc, v51, v34
	v_add_f32_e32 v39, v43, v59
	v_mul_f32_e32 v39, 0x3fb8aa3b, v39
	v_cndmask_b32_e32 v51, 0, v38, vcc
	v_add_f32_e32 v38, v50, v51
	v_add_f32_e32 v50, v37, v38
	v_add_f32_e32 v38, v43, v58
	v_mul_f32_e32 v38, 0x3fb8aa3b, v38
	v_exp_f32_e32 v38, v38
	v_exp_f32_e32 v39, v39
	v_or_b32_e32 v52, 35, v44
	v_or_b32_e32 v53, 34, v44
	v_cmp_le_i32_e32 vcc, v52, v34
	v_pk_mul_f32 v[38:39], v[54:55], v[38:39]
	s_nop 0
	v_cndmask_b32_e32 v39, 0, v39, vcc
	v_cmp_le_i32_e32 vcc, v53, v34
	s_nop 1
	v_cndmask_b32_e32 v52, 0, v38, vcc
	v_add_f32_e32 v38, v52, v50
	v_add_f32_e32 v50, v39, v38
	v_cvt_pk_bf16_f32 v38, v51, v37
	v_cvt_pk_bf16_f32 v39, v52, v39
.LBB0_1340:
	ds_write_b64 v45, v[38:39] offset:64
	s_cmp_lt_i32 s7, 3
	s_cbranch_scc1 .LBB0_1342
	ds_read_b128 v[198:201], v35 offset:47872
	ds_read_b128 v[202:205], v35 offset:47936
	ds_read_b128 v[206:209], v35 offset:48000
	ds_read_b128 v[234:237], v35 offset:48064
	v_or_b32_e32 v56, 48, v44
	v_or_b32_e32 v51, 49, v44
	v_cmp_le_i32_e32 vcc, v51, v34
	s_waitcnt lgkmcnt(3)
	v_mfma_f32_16x16x32_bf16 v[36:39], v[198:201], v[30:33], 0
	s_waitcnt lgkmcnt(2)
	v_mfma_f32_16x16x32_bf16 v[36:39], v[202:205], v[26:29], v[36:39]
	s_waitcnt lgkmcnt(1)
	v_mfma_f32_16x16x32_bf16 v[36:39], v[206:209], v[22:25], v[36:39]
	s_waitcnt lgkmcnt(0)
	v_mfma_f32_16x16x32_bf16 v[36:39], v[234:237], v[18:21], v[36:39]
	v_lshl_add_u32 v52, v56, 2, 0
	v_add_u32_e32 v52, 0x22600, v52
	ds_read_b128 v[52:55], v52
	s_waitcnt lgkmcnt(0)
	v_add_f32_e32 v52, v43, v52
	v_add_f32_e32 v53, v43, v53
	v_mul_f32_e32 v52, 0x3fb8aa3b, v52
	v_mul_f32_e32 v53, 0x3fb8aa3b, v53
	v_exp_f32_e32 v52, v52
	v_exp_f32_e32 v53, v53
	s_nop 0
	v_pk_mul_f32 v[36:37], v[36:37], v[52:53]
	s_nop 0
	v_cndmask_b32_e32 v51, 0, v37, vcc
	v_cmp_le_i32_e32 vcc, v56, v34
	v_add_f32_e32 v37, v43, v55
	v_mul_f32_e32 v37, 0x3fb8aa3b, v37
	v_cndmask_b32_e32 v52, 0, v36, vcc
	v_add_f32_e32 v36, v50, v52
	v_add_f32_e32 v50, v51, v36
	v_add_f32_e32 v36, v43, v54
	v_mul_f32_e32 v36, 0x3fb8aa3b, v36
	v_exp_f32_e32 v36, v36
	v_exp_f32_e32 v37, v37
	v_or_b32_e32 v53, 51, v44
	v_or_b32_e32 v56, 50, v44
	v_cmp_le_i32_e32 vcc, v53, v34
	v_pk_mul_f32 v[36:37], v[38:39], v[36:37]
	s_nop 0
	v_cndmask_b32_e32 v37, 0, v37, vcc
	v_cmp_le_i32_e32 vcc, v56, v34
	s_nop 1
	v_cndmask_b32_e32 v38, 0, v36, vcc
	v_add_f32_e32 v36, v38, v50
	v_add_f32_e32 v50, v37, v36
	v_cvt_pk_bf16_f32 v36, v52, v51
	v_cvt_pk_bf16_f32 v37, v38, v37
	s_branch .LBB0_1343

.LBB0_1343:
	ds_write_b64 v45, v[36:37] offset:96
	v_mov_b32_e32 v36, 0
	s_cmp_lt_i32 s7, 4
	v_mov_b32_e32 v38, 0
	v_mov_b32_e32 v39, 0
	s_cbranch_scc1 .LBB0_1345
	ds_read_b128 v[198:201], v35 offset:52224
	ds_read_b128 v[202:205], v35 offset:52288
	ds_read_b128 v[206:209], v35 offset:52352
	ds_read_b128 v[234:237], v35 offset:52416
	v_or_b32_e32 v51, 64, v44
	v_lshl_add_u32 v38, v51, 2, 0
	v_add_u32_e32 v38, 0x22600, v38
	v_or_b32_e32 v37, 0x41, v44
	v_cmp_le_i32_e32 vcc, v37, v34
	s_waitcnt lgkmcnt(3)
	v_mfma_f32_16x16x32_bf16 v[52:55], v[198:201], v[30:33], 0
	s_waitcnt lgkmcnt(2)
	v_mfma_f32_16x16x32_bf16 v[52:55], v[202:205], v[26:29], v[52:55]
	s_waitcnt lgkmcnt(1)
	v_mfma_f32_16x16x32_bf16 v[52:55], v[206:209], v[22:25], v[52:55]
	s_waitcnt lgkmcnt(0)
	v_mfma_f32_16x16x32_bf16 v[52:55], v[234:237], v[18:21], v[52:55]
	ds_read_b128 v[56:59], v38
	s_waitcnt lgkmcnt(0)
	v_add_f32_e32 v38, v43, v56
	v_add_f32_e32 v39, v43, v57
	v_mul_f32_e32 v38, 0x3fb8aa3b, v38
	v_mul_f32_e32 v39, 0x3fb8aa3b, v39
	v_exp_f32_e32 v38, v38
	v_exp_f32_e32 v39, v39
	s_nop 0
	v_pk_mul_f32 v[38:39], v[52:53], v[38:39]
	s_nop 0
	v_cndmask_b32_e32 v37, 0, v39, vcc
	v_cmp_le_i32_e32 vcc, v51, v34
	v_add_f32_e32 v39, v43, v59
	v_mul_f32_e32 v39, 0x3fb8aa3b, v39
	v_cndmask_b32_e32 v51, 0, v38, vcc
	v_add_f32_e32 v38, v50, v51
	v_add_f32_e32 v50, v37, v38
	v_add_f32_e32 v38, v43, v58
	v_mul_f32_e32 v38, 0x3fb8aa3b, v38
	v_exp_f32_e32 v38, v38
	v_exp_f32_e32 v39, v39
	v_or_b32_e32 v52, 0x43, v44
	v_or_b32_e32 v53, 0x42, v44
	v_cmp_le_i32_e32 vcc, v52, v34
	v_pk_mul_f32 v[38:39], v[54:55], v[38:39]
	s_nop 0
	v_cndmask_b32_e32 v39, 0, v39, vcc
	v_cmp_le_i32_e32 vcc, v53, v34
	s_nop 1
	v_cndmask_b32_e32 v52, 0, v38, vcc
	v_add_f32_e32 v38, v52, v50
	v_add_f32_e32 v50, v39, v38
	v_cvt_pk_bf16_f32 v38, v51, v37
	v_cvt_pk_bf16_f32 v39, v52, v39
.LBB0_1345:
	ds_write_b64 v45, v[38:39] offset:128
	s_cmp_lt_i32 s7, 5
	s_cbranch_scc1 .LBB0_1347
	ds_read_b128 v[198:201], v35 offset:56576
	ds_read_b128 v[202:205], v35 offset:56640
	ds_read_b128 v[206:209], v35 offset:56704
	ds_read_b128 v[234:237], v35 offset:56768
	v_or_b32_e32 v56, 0x50, v44
	v_or_b32_e32 v51, 0x51, v44
	v_cmp_le_i32_e32 vcc, v51, v34
	s_waitcnt lgkmcnt(3)
	v_mfma_f32_16x16x32_bf16 v[36:39], v[198:201], v[30:33], 0
	s_waitcnt lgkmcnt(2)
	v_mfma_f32_16x16x32_bf16 v[36:39], v[202:205], v[26:29], v[36:39]
	s_waitcnt lgkmcnt(1)
	v_mfma_f32_16x16x32_bf16 v[36:39], v[206:209], v[22:25], v[36:39]
	s_waitcnt lgkmcnt(0)
	v_mfma_f32_16x16x32_bf16 v[36:39], v[234:237], v[18:21], v[36:39]
	v_lshl_add_u32 v52, v56, 2, 0
	v_add_u32_e32 v52, 0x22600, v52
	ds_read_b128 v[52:55], v52
	s_waitcnt lgkmcnt(0)
	v_add_f32_e32 v52, v43, v52
	v_add_f32_e32 v53, v43, v53
	v_mul_f32_e32 v52, 0x3fb8aa3b, v52
	v_mul_f32_e32 v53, 0x3fb8aa3b, v53
	v_exp_f32_e32 v52, v52
	v_exp_f32_e32 v53, v53
	s_nop 0
	v_pk_mul_f32 v[36:37], v[36:37], v[52:53]
	s_nop 0
	v_cndmask_b32_e32 v51, 0, v37, vcc
	v_cmp_le_i32_e32 vcc, v56, v34
	v_add_f32_e32 v37, v43, v55
	v_mul_f32_e32 v37, 0x3fb8aa3b, v37
	v_cndmask_b32_e32 v52, 0, v36, vcc
	v_add_f32_e32 v36, v50, v52
	v_add_f32_e32 v50, v51, v36
	v_add_f32_e32 v36, v43, v54
	v_mul_f32_e32 v36, 0x3fb8aa3b, v36
	v_exp_f32_e32 v36, v36
	v_exp_f32_e32 v37, v37
	v_or_b32_e32 v53, 0x53, v44
	v_or_b32_e32 v56, 0x52, v44
	v_cmp_le_i32_e32 vcc, v53, v34
	v_pk_mul_f32 v[36:37], v[38:39], v[36:37]
	s_nop 0
	v_cndmask_b32_e32 v37, 0, v37, vcc
	v_cmp_le_i32_e32 vcc, v56, v34
	s_nop 1
	v_cndmask_b32_e32 v38, 0, v36, vcc
	v_add_f32_e32 v36, v38, v50
	v_add_f32_e32 v50, v37, v36
	v_cvt_pk_bf16_f32 v36, v52, v51
	v_cvt_pk_bf16_f32 v37, v38, v37
	s_branch .LBB0_1348

.LBB0_1348:
	ds_write_b64 v45, v[36:37] offset:160
	v_mov_b32_e32 v36, 0
	s_cmp_lt_i32 s7, 6
	v_mov_b32_e32 v38, 0
	v_mov_b32_e32 v39, 0
	s_cbranch_scc1 .LBB0_1350
	ds_read_b128 v[198:201], v35 offset:60928
	ds_read_b128 v[202:205], v35 offset:60992
	ds_read_b128 v[206:209], v35 offset:61056
	ds_read_b128 v[234:237], v35 offset:61120
	v_or_b32_e32 v51, 0x60, v44
	v_lshl_add_u32 v38, v51, 2, 0
	v_add_u32_e32 v38, 0x22600, v38
	v_or_b32_e32 v37, 0x61, v44
	v_cmp_le_i32_e32 vcc, v37, v34
	s_waitcnt lgkmcnt(3)
	v_mfma_f32_16x16x32_bf16 v[52:55], v[198:201], v[30:33], 0
	s_waitcnt lgkmcnt(2)
	v_mfma_f32_16x16x32_bf16 v[52:55], v[202:205], v[26:29], v[52:55]
	s_waitcnt lgkmcnt(1)
	v_mfma_f32_16x16x32_bf16 v[52:55], v[206:209], v[22:25], v[52:55]
	s_waitcnt lgkmcnt(0)
	v_mfma_f32_16x16x32_bf16 v[52:55], v[234:237], v[18:21], v[52:55]
	ds_read_b128 v[56:59], v38
	s_waitcnt lgkmcnt(0)
	v_add_f32_e32 v38, v43, v56
	v_add_f32_e32 v39, v43, v57
	v_mul_f32_e32 v38, 0x3fb8aa3b, v38
	v_mul_f32_e32 v39, 0x3fb8aa3b, v39
	v_exp_f32_e32 v38, v38
	v_exp_f32_e32 v39, v39
	s_nop 0
	v_pk_mul_f32 v[38:39], v[52:53], v[38:39]
	s_nop 0
	v_cndmask_b32_e32 v37, 0, v39, vcc
	v_cmp_le_i32_e32 vcc, v51, v34
	v_add_f32_e32 v39, v43, v59
	v_mul_f32_e32 v39, 0x3fb8aa3b, v39
	v_cndmask_b32_e32 v51, 0, v38, vcc
	v_add_f32_e32 v38, v50, v51
	v_add_f32_e32 v50, v37, v38
	v_add_f32_e32 v38, v43, v58
	v_mul_f32_e32 v38, 0x3fb8aa3b, v38
	v_exp_f32_e32 v38, v38
	v_exp_f32_e32 v39, v39
	v_or_b32_e32 v52, 0x63, v44
	v_or_b32_e32 v53, 0x62, v44
	v_cmp_le_i32_e32 vcc, v52, v34
	v_pk_mul_f32 v[38:39], v[54:55], v[38:39]
	s_nop 0
	v_cndmask_b32_e32 v39, 0, v39, vcc
	v_cmp_le_i32_e32 vcc, v53, v34
	s_nop 1
	v_cndmask_b32_e32 v52, 0, v38, vcc
	v_add_f32_e32 v38, v52, v50
	v_add_f32_e32 v50, v39, v38
	v_cvt_pk_bf16_f32 v38, v51, v37
	v_cvt_pk_bf16_f32 v39, v52, v39
.LBB0_1350:
	ds_write_b64 v45, v[38:39] offset:192
	s_cmp_lt_i32 s7, 7
	s_cbranch_scc1 .LBB0_1352
	ds_read_b128 v[198:201], v35 offset:65280
	s_waitcnt lgkmcnt(0)
	v_mfma_f32_16x16x32_bf16 v[30:33], v[198:201], v[30:33], 0
	ds_read_b128 v[36:39], v35 offset:65344
	s_waitcnt lgkmcnt(0)
	v_mfma_f32_16x16x32_bf16 v[26:29], v[36:39], v[26:29], v[30:33]
	s_nop 4
	ds_read_b128 v[30:33], v35 offset:65408
	s_waitcnt lgkmcnt(0)
	v_mfma_f32_16x16x32_bf16 v[22:25], v[30:33], v[22:25], v[26:29]
	s_nop 2
	ds_read_b128 v[26:29], v35 offset:65472
	s_waitcnt lgkmcnt(0)
	v_mfma_f32_16x16x32_bf16 v[18:21], v[26:29], v[18:21], v[22:25]
	v_or_b32_e32 v27, 0x70, v44
	s_nop 1
	v_lshl_add_u32 v22, v27, 2, 0
	v_add_u32_e32 v22, 0x22600, v22
	ds_read_b128 v[22:25], v22
	v_or_b32_e32 v26, 0x71, v44
	v_cmp_le_i32_e32 vcc, v26, v34
	v_or_b32_e32 v28, 0x72, v44
	s_waitcnt lgkmcnt(0)
	v_add_f32_e32 v22, v43, v22
	v_add_f32_e32 v23, v43, v23
	v_mul_f32_e32 v22, 0x3fb8aa3b, v22
	v_mul_f32_e32 v23, 0x3fb8aa3b, v23
	v_exp_f32_e32 v22, v22
	v_exp_f32_e32 v23, v23
	s_nop 0
	v_pk_mul_f32 v[18:19], v[18:19], v[22:23]
	s_nop 0
	v_cndmask_b32_e32 v22, 0, v19, vcc
	v_cmp_le_i32_e32 vcc, v27, v34
	v_add_f32_e32 v19, v43, v25
	v_mul_f32_e32 v19, 0x3fb8aa3b, v19
	v_cndmask_b32_e32 v23, 0, v18, vcc
	v_add_f32_e32 v18, v50, v23
	v_add_f32_e32 v26, v22, v18
	v_add_f32_e32 v18, v43, v24
	v_mul_f32_e32 v18, 0x3fb8aa3b, v18
	v_exp_f32_e32 v18, v18
	v_exp_f32_e32 v19, v19
	v_or_b32_e32 v27, 0x73, v44
	v_cmp_le_i32_e32 vcc, v27, v34
	v_cvt_pk_bf16_f32 v36, v23, v22
	v_pk_mul_f32 v[18:19], v[20:21], v[18:19]
	s_nop 0
	v_cndmask_b32_e32 v19, 0, v19, vcc
	v_cmp_le_i32_e32 vcc, v28, v34
	s_nop 1
	v_cndmask_b32_e32 v18, 0, v18, vcc
	v_add_f32_e32 v20, v18, v26
	v_add_f32_e32 v50, v19, v20
	v_cvt_pk_bf16_f32 v37, v18, v19
	s_branch .LBB0_1353

.LBB0_1355:
	s_or_b64 exec, exec, s[4:5]
	s_waitcnt lgkmcnt(0)
	s_barrier
	ds_read_b128 v[202:205], v35 offset:64
	ds_read_b128 v[206:209], v35
	ds_read_b128 v[234:237], v35 offset:128
	ds_read_b128 v[238:241], v35 offset:192
	v_add_u32_e32 v88, s34, v0
	v_mad_u32_u24 v0, v86, s46, v88
	ds_read_b128 v[198:201], v0
	s_waitcnt lgkmcnt(5)
	v_lshl_add_u32 v0, v86, 2, 0
	s_waitcnt lgkmcnt(0)
	v_mfma_f32_16x16x32_bf16 v[90:93], v[14:17], v[198:201], 0
	v_add_u32_e32 v0, 0x22000, v0
	v_add_u32_e32 v50, 64, v0
	s_waitcnt vmcnt(3) lgkmcnt(0)
	v_mfma_f32_16x16x32_bf16 v[18:21], v[82:85], v[206:209], 0
	v_add_u32_e32 v89, 0x80, v0
	v_add_u32_e32 v104, 0xc0, v0
	s_and_b64 s[4:5], s[56:57], exec
	s_waitcnt vmcnt(2)
	v_mfma_f32_16x16x32_bf16 v[18:21], v[78:81], v[202:205], v[18:21]
	s_mov_b32 s5, s3
	s_mov_b32 s7, -1
	s_waitcnt vmcnt(1) lgkmcnt(0)
	v_mfma_f32_16x16x32_bf16 v[18:21], v[74:77], v[234:237], v[18:21]
	ds_read2st64_b32 v[114:115], v0 offset0:12 offset1:14
	ds_read2st64_b32 v[116:117], v0 offset1:2
	s_waitcnt vmcnt(0) lgkmcnt(2)
	v_mfma_f32_16x16x32_bf16 v[94:97], v[46:49], v[238:241], v[18:21]
	s_cselect_b32 s4, 1, 19
	s_nop 1
	v_mov_b32_e32 v18, 0x1100
	v_mad_u32_u24 v22, v86, s46, v18
	v_add_u32_e32 v18, v88, v22
	ds_read_b128 v[242:245], v18
	v_add_u32_e32 v26, v87, v22
	ds_read_b128 v[246:249], v26 offset:64
	ds_read_b128 v[250:253], v26
	ds_read_b128 v[198:201], v26 offset:128
	ds_read_b128 v[202:205], v26 offset:192
	s_waitcnt lgkmcnt(4)
	v_mfma_f32_16x16x32_bf16 v[42:45], v[14:17], v[242:245], 0
	s_waitcnt lgkmcnt(2)
	v_mfma_f32_16x16x32_bf16 v[18:21], v[82:85], v[250:253], 0
	v_mfma_f32_16x16x32_bf16 v[18:21], v[78:81], v[246:249], v[18:21]
	s_waitcnt lgkmcnt(1)
	v_mfma_f32_16x16x32_bf16 v[18:21], v[74:77], v[198:201], v[18:21]
	ds_read2st64_b32 v[142:143], v50 offset0:12 offset1:14
	ds_read2_b32 v[156:157], v0 offset0:16 offset1:144
	s_waitcnt lgkmcnt(2)
	v_mfma_f32_16x16x32_bf16 v[70:73], v[46:49], v[202:205], v[18:21]
	s_nop 2
	v_mov_b32_e32 v18, 0x2200
	v_mad_u32_u24 v26, v86, s46, v18
	v_add_u32_e32 v22, v88, v26
	ds_read_b128 v[206:209], v22
	ds_read_b128 v[234:237], v22 offset:64
	s_waitcnt lgkmcnt(1)
	v_mfma_f32_16x16x32_bf16 v[18:21], v[14:17], v[206:209], 0
	v_add_u32_e32 v26, v87, v26
	ds_read_b128 v[238:241], v26 offset:64
	ds_read_b128 v[242:245], v26
	ds_read_b128 v[246:249], v26 offset:128
	ds_read_b128 v[250:253], v26 offset:192
	s_waitcnt lgkmcnt(4)
	v_mfma_f32_16x16x32_bf16 v[38:41], v[10:13], v[234:237], v[18:21]
	s_nop 3
	s_waitcnt lgkmcnt(2)
	v_mfma_f32_16x16x32_bf16 v[18:21], v[82:85], v[242:245], 0
	v_mfma_f32_16x16x32_bf16 v[18:21], v[78:81], v[238:241], v[18:21]
	s_waitcnt lgkmcnt(1)
	v_mfma_f32_16x16x32_bf16 v[18:21], v[74:77], v[246:249], v[18:21]
	ds_read2st64_b32 v[140:141], v89 offset0:12 offset1:14
	ds_read2_b32 v[154:155], v0 offset0:32 offset1:160
	s_waitcnt lgkmcnt(2)
	v_mfma_f32_16x16x32_bf16 v[66:69], v[46:49], v[250:253], v[18:21]
	s_nop 2
	v_mov_b32_e32 v18, 0x3300
	v_mad_u32_u24 v26, v86, s46, v18
	v_add_u32_e32 v22, v88, v26
	ds_read_b128 v[198:201], v22
	ds_read_b128 v[202:205], v22 offset:64
	s_waitcnt lgkmcnt(1)
	v_mfma_f32_16x16x32_bf16 v[18:21], v[14:17], v[198:201], 0
	v_add_u32_e32 v26, v87, v26
	ds_read_b128 v[206:209], v26 offset:64
	ds_read_b128 v[234:237], v26
	ds_read_b128 v[238:241], v26 offset:128
	ds_read_b128 v[242:245], v26 offset:192
	s_waitcnt lgkmcnt(4)
	v_mfma_f32_16x16x32_bf16 v[34:37], v[10:13], v[202:205], v[18:21]
	s_nop 3
	s_waitcnt lgkmcnt(2)
	v_mfma_f32_16x16x32_bf16 v[18:21], v[82:85], v[234:237], 0
	v_mfma_f32_16x16x32_bf16 v[18:21], v[78:81], v[206:209], v[18:21]
	s_waitcnt lgkmcnt(1)
	v_mfma_f32_16x16x32_bf16 v[18:21], v[74:77], v[238:241], v[18:21]
	ds_read2st64_b32 v[138:139], v104 offset0:12 offset1:14
	ds_read2_b32 v[152:153], v0 offset0:48 offset1:176
	s_waitcnt lgkmcnt(2)
	v_mfma_f32_16x16x32_bf16 v[58:61], v[46:49], v[242:245], v[18:21]
	s_nop 2
	v_mov_b32_e32 v18, 0x4400
	v_mad_u32_u24 v26, v86, s46, v18
	v_add_u32_e32 v27, v88, v26
	ds_read_b128 v[246:249], v27
	ds_read_b128 v[250:253], v27 offset:64
	ds_read_b128 v[198:201], v27 offset:128
	s_waitcnt lgkmcnt(2)
	v_mfma_f32_16x16x32_bf16 v[18:21], v[14:17], v[246:249], 0
	v_add_u32_e32 v30, v87, v26
	ds_read_b128 v[202:205], v30 offset:64
	ds_read_b128 v[206:209], v30
	ds_read_b128 v[234:237], v30 offset:128
	ds_read_b128 v[238:241], v30 offset:192
	s_waitcnt lgkmcnt(5)
	v_mfma_f32_16x16x32_bf16 v[18:21], v[10:13], v[250:253], v[18:21]
	s_waitcnt lgkmcnt(4)
	v_mfma_f32_16x16x32_bf16 v[22:25], v[6:9], v[198:201], v[18:21]
	s_nop 3
	s_waitcnt lgkmcnt(2)
	v_mfma_f32_16x16x32_bf16 v[18:21], v[82:85], v[206:209], 0
	v_mfma_f32_16x16x32_bf16 v[18:21], v[78:81], v[202:205], v[18:21]
	s_waitcnt lgkmcnt(1)
	v_mfma_f32_16x16x32_bf16 v[18:21], v[74:77], v[234:237], v[18:21]
	ds_read2st64_b32 v[136:137], v0 offset0:13 offset1:15
	ds_read2st64_b32 v[150:151], v0 offset0:1 offset1:3
	s_waitcnt lgkmcnt(2)
	v_mfma_f32_16x16x32_bf16 v[62:65], v[46:49], v[238:241], v[18:21]
	s_nop 2
	v_mov_b32_e32 v18, 0x5500
	v_mad_u32_u24 v30, v86, s46, v18
	v_add_u32_e32 v31, v88, v30
	ds_read_b128 v[242:245], v31
	ds_read_b128 v[246:249], v31 offset:64
	ds_read_b128 v[250:253], v31 offset:128
	s_waitcnt lgkmcnt(2)
	v_mfma_f32_16x16x32_bf16 v[18:21], v[14:17], v[242:245], 0
	v_add_u32_e32 v51, v87, v30
	ds_read_b128 v[198:201], v51 offset:64
	ds_read_b128 v[202:205], v51
	ds_read_b128 v[206:209], v51 offset:128
	ds_read_b128 v[234:237], v51 offset:192
	s_waitcnt lgkmcnt(5)
	v_mfma_f32_16x16x32_bf16 v[18:21], v[10:13], v[246:249], v[18:21]
	s_waitcnt lgkmcnt(4)
	v_mfma_f32_16x16x32_bf16 v[18:21], v[6:9], v[250:253], v[18:21]
	s_waitcnt lgkmcnt(2)
	v_mfma_f32_16x16x32_bf16 v[26:29], v[82:85], v[202:205], 0
	v_mfma_f32_16x16x32_bf16 v[26:29], v[78:81], v[198:201], v[26:29]
	s_waitcnt lgkmcnt(1)
	v_mfma_f32_16x16x32_bf16 v[26:29], v[74:77], v[206:209], v[26:29]
	ds_read2st64_b32 v[134:135], v50 offset0:13 offset1:15
	ds_read2_b32 v[148:149], v0 offset0:80 offset1:208
	s_waitcnt lgkmcnt(2)
	v_mfma_f32_16x16x32_bf16 v[54:57], v[46:49], v[234:237], v[26:29]
	s_nop 2
	v_mov_b32_e32 v26, 0x6600
	v_mad_u32_u24 v50, v86, s46, v26
	v_add_u32_e32 v51, v88, v50
	ds_read_b128 v[238:241], v51
	ds_read_b128 v[242:245], v51 offset:64
	ds_read_b128 v[246:249], v51 offset:128
	ds_read_b128 v[250:253], v51 offset:192
	s_waitcnt lgkmcnt(3)
	v_mfma_f32_16x16x32_bf16 v[26:29], v[14:17], v[238:241], 0
	v_add_u32_e32 v100, v87, v50
	ds_read_b128 v[198:201], v100 offset:64
	ds_read_b128 v[202:205], v100
	ds_read_b128 v[206:209], v100 offset:128
	ds_read_b128 v[234:237], v100 offset:192
	s_waitcnt lgkmcnt(6)
	v_mfma_f32_16x16x32_bf16 v[26:29], v[10:13], v[242:245], v[26:29]
	s_waitcnt lgkmcnt(5)
	v_mfma_f32_16x16x32_bf16 v[26:29], v[6:9], v[246:249], v[26:29]
	s_waitcnt lgkmcnt(4)
	v_mfma_f32_16x16x32_bf16 v[30:33], v[2:5], v[250:253], v[26:29]
	s_nop 3
	s_waitcnt lgkmcnt(2)
	v_mfma_f32_16x16x32_bf16 v[26:29], v[82:85], v[202:205], 0
	v_mfma_f32_16x16x32_bf16 v[26:29], v[78:81], v[198:201], v[26:29]
	s_waitcnt lgkmcnt(1)
	v_mfma_f32_16x16x32_bf16 v[26:29], v[74:77], v[206:209], v[26:29]
	ds_read2st64_b32 v[128:129], v89 offset0:13 offset1:15
	ds_read2_b32 v[146:147], v0 offset0:96 offset1:224
	s_waitcnt lgkmcnt(2)
	v_mfma_f32_16x16x32_bf16 v[50:53], v[46:49], v[234:237], v[26:29]
	s_nop 2
	v_mov_b32_e32 v26, 0x7700
	v_mad_u32_u24 v86, v86, s46, v26
	v_add_u32_e32 v88, v88, v86
	ds_read_b128 v[238:241], v88
	ds_read_b128 v[242:245], v88 offset:64
	ds_read_b128 v[246:249], v88 offset:128
	s_waitcnt lgkmcnt(2)
	v_mfma_f32_16x16x32_bf16 v[26:29], v[14:17], v[238:241], 0
	s_waitcnt lgkmcnt(1)
	v_mfma_f32_16x16x32_bf16 v[26:29], v[10:13], v[242:245], v[26:29]
	s_waitcnt lgkmcnt(0)
	v_mfma_f32_16x16x32_bf16 v[26:29], v[6:9], v[246:249], v[26:29]
	ds_read_b128 v[100:103], v88 offset:192
	s_waitcnt lgkmcnt(0)
	v_mfma_f32_16x16x32_bf16 v[26:29], v[2:5], v[100:103], v[26:29]
	v_add_u32_e32 v100, v87, v86
	ds_read_b128 v[250:253], v100
	s_waitcnt lgkmcnt(0)
	v_mfma_f32_16x16x32_bf16 v[82:85], v[82:85], v[250:253], 0
	ds_read_b128 v[86:89], v100 offset:64
	s_waitcnt lgkmcnt(0)
	v_mfma_f32_16x16x32_bf16 v[78:81], v[78:81], v[86:89], v[82:85]
	s_nop 4
	ds_read_b128 v[82:85], v100 offset:128
	s_waitcnt lgkmcnt(0)
	v_mfma_f32_16x16x32_bf16 v[74:77], v[74:77], v[82:85], v[78:81]
	s_nop 2
	ds_read_b128 v[78:81], v100 offset:192
	ds_read2st64_b32 v[126:127], v104 offset0:13 offset1:15
	ds_read2_b32 v[144:145], v0 offset0:112 offset1:240
	s_waitcnt lgkmcnt(0)
	s_barrier
	s_waitcnt lgkmcnt(2)
	v_mfma_f32_16x16x32_bf16 v[46:49], v[46:49], v[78:81], v[74:77]
	v_mbcnt_lo_u32_b32 v0, s7, 0
	v_mbcnt_hi_u32_b32 v0, s7, v0
	v_lshl_add_u32 v101, s5, 6, v0
	s_nop 0
	v_readfirstlane_b32 s5, v101
	s_ashr_i32 s7, s5, 6
	s_sub_i32 s5, s6, s90
	s_add_i32 s4, s5, s4
	s_addk_i32 s4, 0x48
	v_and_b32_e32 v191, 15, v101
	s_ashr_i32 s5, s4, 31
	s_lshl_b64 s[4:5], s[4:5], 15
	v_lshl_or_b32 v118, s7, 4, v191
	s_add_u32 s4, s86, s4
	v_ashrrev_i32_e32 v119, 31, v118
	v_bfe_u32 v124, v101, 4, 2
	s_addc_u32 s5, s87, s5
	v_lshlrev_b64 v[74:75], 8, v[118:119]
	v_lshl_add_u64 v[74:75], s[4:5], 0, v[74:75]
	v_lshlrev_b32_e32 v0, 4, v124
	v_lshl_add_u64 v[74:75], v[74:75], 0, v[0:1]
	global_load_dwordx4 v[86:89], v[74:75], off
	global_load_dwordx4 v[82:85], v[74:75], off offset:64
	global_load_dwordx4 v[78:81], v[74:75], off offset:128
	s_nop 0
	global_load_dwordx4 v[74:77], v[74:75], off offset:192
	v_ashrrev_i32_e32 v100, 2, v101
	v_and_b32_e32 v101, 3, v101
	v_mul_lo_u32 v102, v100, s46
	v_lshlrev_b32_e32 v103, 6, v101
	v_add3_u32 v119, 0, v102, v103
	v_lshl_add_u32 v102, v101, 7, 0
	v_add_u32_e32 v125, 0x24200, v102
	ds_read_b128 v[102:105], v119
	ds_read_b128 v[106:109], v119 offset:16
	ds_read_b128 v[110:113], v119 offset:32
	ds_read_b128 v[120:123], v119 offset:48
	ds_read_b128 v[158:161], v125
	ds_read_b128 v[162:165], v125 offset:16
	ds_read_b128 v[166:169], v125 offset:32
	ds_read_b128 v[170:173], v125 offset:48
	s_waitcnt lgkmcnt(7)
	v_lshlrev_b32_e32 v119, 16, v102
	v_and_b32_e32 v102, 0xffff0000, v102
	s_waitcnt lgkmcnt(3)
	v_mul_f32_e32 v102, v159, v102
	v_fmac_f32_e32 v102, v158, v119
	v_lshlrev_b32_e32 v119, 16, v103
	v_fmac_f32_e32 v102, v160, v119
	v_and_b32_e32 v103, 0xffff0000, v103
	v_fmac_f32_e32 v102, v161, v103
	v_lshlrev_b32_e32 v103, 16, v104
	s_waitcnt lgkmcnt(2)
	v_fmac_f32_e32 v102, v162, v103
	v_and_b32_e32 v103, 0xffff0000, v104
	v_fmac_f32_e32 v102, v163, v103
	v_lshlrev_b32_e32 v103, 16, v105
	v_fmac_f32_e32 v102, v164, v103
	v_and_b32_e32 v103, 0xffff0000, v105
	v_and_b32_e32 v104, 0xffff0000, v106
	v_fmac_f32_e32 v102, v165, v103
	v_lshlrev_b32_e32 v103, 16, v106
	s_waitcnt lgkmcnt(1)
	v_mul_f32_e32 v104, v167, v104
	v_fmac_f32_e32 v104, v166, v103
	v_lshlrev_b32_e32 v103, 16, v107
	v_fmac_f32_e32 v104, v168, v103
	v_and_b32_e32 v103, 0xffff0000, v107
	v_fmac_f32_e32 v104, v169, v103
	v_lshlrev_b32_e32 v103, 16, v108
	s_waitcnt lgkmcnt(0)
	v_fmac_f32_e32 v104, v170, v103
	v_and_b32_e32 v103, 0xffff0000, v108
	v_fmac_f32_e32 v104, v171, v103
	v_lshlrev_b32_e32 v103, 16, v109
	v_fmac_f32_e32 v104, v172, v103
	v_and_b32_e32 v103, 0xffff0000, v109
	v_add_f32_e32 v102, 0, v102
	v_fmac_f32_e32 v104, v173, v103
	v_add_f32_e32 v106, v102, v104
	ds_read_b128 v[102:105], v125 offset:64
	v_and_b32_e32 v108, 0xffff0000, v110
	v_lshlrev_b32_e32 v107, 16, v110
	v_cmp_eq_u32_e32 vcc, 0, v101
	s_waitcnt lgkmcnt(0)
	v_mul_f32_e32 v108, v103, v108
	v_fmac_f32_e32 v108, v102, v107
	v_lshlrev_b32_e32 v102, 16, v111
	v_fmac_f32_e32 v108, v104, v102
	v_and_b32_e32 v102, 0xffff0000, v111
	v_fmac_f32_e32 v108, v105, v102
	ds_read_b128 v[102:105], v125 offset:80
	v_lshlrev_b32_e32 v107, 16, v112
	s_waitcnt lgkmcnt(0)
	v_fmac_f32_e32 v108, v102, v107
	v_and_b32_e32 v102, 0xffff0000, v112
	v_fmac_f32_e32 v108, v103, v102
	v_lshlrev_b32_e32 v102, 16, v113
	v_fmac_f32_e32 v108, v104, v102
	v_and_b32_e32 v102, 0xffff0000, v113
	v_fmac_f32_e32 v108, v105, v102
	ds_read_b128 v[102:105], v125 offset:96
	v_add_f32_e32 v106, v106, v108
	v_and_b32_e32 v108, 0xffff0000, v120
	v_lshlrev_b32_e32 v107, 16, v120
	s_waitcnt lgkmcnt(0)
	v_mul_f32_e32 v108, v103, v108
	v_fmac_f32_e32 v108, v102, v107
	v_lshlrev_b32_e32 v102, 16, v121
	v_fmac_f32_e32 v108, v104, v102
	v_and_b32_e32 v102, 0xffff0000, v121
	v_fmac_f32_e32 v108, v105, v102
	ds_read_b128 v[102:105], v125 offset:112
	v_lshlrev_b32_e32 v107, 16, v122
	s_waitcnt lgkmcnt(0)
	v_fmac_f32_e32 v108, v102, v107
	v_and_b32_e32 v102, 0xffff0000, v122
	v_fmac_f32_e32 v108, v103, v102
	v_lshlrev_b32_e32 v102, 16, v123
	v_fmac_f32_e32 v108, v104, v102
	v_and_b32_e32 v102, 0xffff0000, v123
	v_fmac_f32_e32 v108, v105, v102
	v_add_f32_e32 v102, v106, v108
	ds_bpermute_b32 v98, v98, v102
	s_waitcnt lgkmcnt(0)
	v_add_f32_e32 v98, v102, v98
	ds_bpermute_b32 v99, v99, v98
	s_and_saveexec_b64 s[4:5], vcc
	s_cbranch_execz .LBB0_1357
	v_sub_u32_e32 v100, 0x7f, v100
	v_lshl_add_u32 v100, v100, 2, s39
	s_waitcnt lgkmcnt(0)
	v_add_f32_e32 v98, v98, v99
	ds_write_b32 v100, v98 offset:512
.LBB0_1357:
	s_or_b64 exec, exec, s[4:5]
	v_mul_lo_u32 v121, v118, s46
	v_add_u32_e32 v159, 0, v0
	s_waitcnt lgkmcnt(0)
	v_sub_u32_e32 v99, 0x7f, v118
	v_add_u32_e32 v98, v159, v121
	v_lshl_add_u32 v119, v99, 2, s39
	ds_read2st64_b32 v[122:123], v119 offset0:4 offset1:10
	ds_read_b128 v[110:113], v98
	ds_read_b128 v[106:109], v98 offset:64
	ds_read_b128 v[102:105], v98 offset:128
	ds_read_b128 v[98:101], v98 offset:192
	s_waitcnt lgkmcnt(4)
	v_sub_f32_e32 v125, v122, v123
	v_lshlrev_b32_e32 v158, 2, v124
	v_mov_b32_e32 v120, 0
	v_mov_b32_e32 v122, 0
	s_cmp_gt_i32 s7, 0
	v_mad_u32_u24 v192, v191, s46, v159
	v_mov_b32_e32 v123, 0
	v_mov_b32_e32 v160, 0
	s_cbranch_scc1 .LBB0_1359
	ds_read_b128 v[198:201], v192 offset:34816
	ds_read_b128 v[202:205], v192 offset:34880
	ds_read_b128 v[206:209], v192 offset:34944
	ds_read_b128 v[234:237], v192 offset:35008
	v_lshlrev_b32_e32 v122, 2, v158
	v_sub_u32_e32 v122, 0, v122
	v_add_u32_e32 v122, 0x239f0, v122
	v_or_b32_e32 v159, 1, v158
	v_cmp_ge_i32_e32 vcc, v159, v118
	s_waitcnt lgkmcnt(3)
	v_mfma_f32_16x16x32_bf16 v[160:163], v[198:201], v[110:113], 0
	s_waitcnt lgkmcnt(2)
	v_mfma_f32_16x16x32_bf16 v[160:163], v[202:205], v[106:109], v[160:163]
	s_waitcnt lgkmcnt(1)
	v_mfma_f32_16x16x32_bf16 v[160:163], v[206:209], v[102:105], v[160:163]
	s_waitcnt lgkmcnt(0)
	v_mfma_f32_16x16x32_bf16 v[160:163], v[234:237], v[98:101], v[160:163]
	ds_read_b128 v[164:167], v122
	s_waitcnt lgkmcnt(0)
	v_add_f32_e32 v122, v125, v167
	v_add_f32_e32 v123, v125, v166
	v_mul_f32_e32 v122, 0x3fb8aa3b, v122
	v_mul_f32_e32 v123, 0x3fb8aa3b, v123
	v_exp_f32_e32 v122, v122
	v_exp_f32_e32 v123, v123
	v_or_b32_e32 v166, 3, v158
	v_or_b32_e32 v167, 2, v158
	v_pk_mul_f32 v[122:123], v[160:161], v[122:123]
	s_nop 0
	v_cndmask_b32_e32 v159, 0, v123, vcc
	v_cmp_ge_i32_e32 vcc, v158, v118
	v_add_f32_e32 v123, v125, v164
	v_mul_f32_e32 v123, 0x3fb8aa3b, v123
	v_cndmask_b32_e32 v161, 0, v122, vcc
	v_add_f32_e32 v122, 0, v161
	v_add_f32_e32 v160, v159, v122
	v_add_f32_e32 v122, v125, v165
	v_mul_f32_e32 v122, 0x3fb8aa3b, v122
	v_exp_f32_e32 v122, v122
	v_exp_f32_e32 v123, v123
	v_cmp_ge_i32_e32 vcc, v166, v118
	v_pk_mul_f32 v[122:123], v[162:163], v[122:123]
	s_nop 0
	v_cndmask_b32_e32 v123, 0, v123, vcc
	v_cmp_ge_i32_e32 vcc, v167, v118
	s_nop 1
	v_cndmask_b32_e32 v162, 0, v122, vcc
	v_add_f32_e32 v122, v162, v160
	v_add_f32_e32 v160, v123, v122
	v_cvt_pk_bf16_f32 v122, v161, v159
	v_cvt_pk_bf16_f32 v123, v162, v123
.LBB0_1359:
	v_lshlrev_b32_e32 v159, 3, v124
	v_add_u32_e32 v121, s34, v121
	v_add_u32_e32 v159, v121, v159
	ds_write_b64 v159, v[122:123]
	s_cmp_gt_i32 s7, 1
	s_cbranch_scc1 .LBB0_1361
	ds_read_b128 v[198:201], v192 offset:39168
	ds_read_b128 v[202:205], v192 offset:39232
	ds_read_b128 v[206:209], v192 offset:39296
	ds_read_b128 v[234:237], v192 offset:39360
	v_or_b32_e32 v168, 16, v158
	v_or_b32_e32 v161, 17, v158
	v_cmp_ge_i32_e32 vcc, v161, v118
	s_waitcnt lgkmcnt(3)
	v_mfma_f32_16x16x32_bf16 v[120:123], v[198:201], v[110:113], 0
	s_waitcnt lgkmcnt(2)
	v_mfma_f32_16x16x32_bf16 v[120:123], v[202:205], v[106:109], v[120:123]
	s_waitcnt lgkmcnt(1)
	v_mfma_f32_16x16x32_bf16 v[120:123], v[206:209], v[102:105], v[120:123]
	s_waitcnt lgkmcnt(0)
	v_mfma_f32_16x16x32_bf16 v[120:123], v[234:237], v[98:101], v[120:123]
	v_lshlrev_b32_e32 v162, 2, v168
	v_sub_u32_e32 v162, 0, v162
	v_add_u32_e32 v162, 0x239f0, v162
	ds_read_b128 v[162:165], v162
	s_waitcnt lgkmcnt(0)
	v_add_f32_e32 v165, v125, v165
	v_add_f32_e32 v164, v125, v164
	v_mul_f32_e32 v165, 0x3fb8aa3b, v165
	v_mul_f32_e32 v164, 0x3fb8aa3b, v164
	v_exp_f32_e32 v166, v165
	v_exp_f32_e32 v167, v164
	v_or_b32_e32 v165, 19, v158
	v_pk_mul_f32 v[120:121], v[120:121], v[166:167]
	s_nop 0
	v_cndmask_b32_e32 v161, 0, v121, vcc
	v_cmp_ge_i32_e32 vcc, v168, v118
	v_add_f32_e32 v121, v125, v162
	v_mul_f32_e32 v121, 0x3fb8aa3b, v121
	v_cndmask_b32_e32 v164, 0, v120, vcc
	v_add_f32_e32 v120, v160, v164
	v_add_f32_e32 v160, v161, v120
	v_add_f32_e32 v120, v125, v163
	v_mul_f32_e32 v120, 0x3fb8aa3b, v120
	v_exp_f32_e32 v120, v120
	v_exp_f32_e32 v121, v121
	v_or_b32_e32 v166, 18, v158
	v_cmp_ge_i32_e32 vcc, v165, v118
	v_pk_mul_f32 v[120:121], v[122:123], v[120:121]
	s_nop 0
	v_cndmask_b32_e32 v121, 0, v121, vcc
	v_cmp_ge_i32_e32 vcc, v166, v118
	s_nop 1
	v_cndmask_b32_e32 v122, 0, v120, vcc
	v_add_f32_e32 v120, v122, v160
	v_add_f32_e32 v160, v121, v120
	v_cvt_pk_bf16_f32 v120, v164, v161
	v_cvt_pk_bf16_f32 v121, v122, v121
	s_branch .LBB0_1362

.LBB0_1362:
	ds_write_b64 v159, v[120:121] offset:32
	v_mov_b32_e32 v120, 0
	s_cmp_gt_i32 s7, 2
	v_mov_b32_e32 v122, 0
	v_mov_b32_e32 v123, 0
	s_cbranch_scc1 .LBB0_1364
	ds_read_b128 v[198:201], v192 offset:43520
	ds_read_b128 v[202:205], v192 offset:43584
	ds_read_b128 v[206:209], v192 offset:43648
	ds_read_b128 v[234:237], v192 offset:43712
	v_or_b32_e32 v161, 32, v158
	v_lshlrev_b32_e32 v122, 2, v161
	v_sub_u32_e32 v122, 0, v122
	v_add_u32_e32 v122, 0x239f0, v122
	v_or_b32_e32 v121, 33, v158
	v_cmp_ge_i32_e32 vcc, v121, v118
	s_waitcnt lgkmcnt(3)
	v_mfma_f32_16x16x32_bf16 v[162:165], v[198:201], v[110:113], 0
	s_waitcnt lgkmcnt(2)
	v_mfma_f32_16x16x32_bf16 v[162:165], v[202:205], v[106:109], v[162:165]
	s_waitcnt lgkmcnt(1)
	v_mfma_f32_16x16x32_bf16 v[162:165], v[206:209], v[102:105], v[162:165]
	s_waitcnt lgkmcnt(0)
	v_mfma_f32_16x16x32_bf16 v[162:165], v[234:237], v[98:101], v[162:165]
	ds_read_b128 v[166:169], v122
	s_waitcnt lgkmcnt(0)
	v_add_f32_e32 v122, v125, v169
	v_add_f32_e32 v123, v125, v168
	v_mul_f32_e32 v122, 0x3fb8aa3b, v122
	v_mul_f32_e32 v123, 0x3fb8aa3b, v123
	v_exp_f32_e32 v122, v122
	v_exp_f32_e32 v123, v123
	s_nop 0
	v_pk_mul_f32 v[122:123], v[162:163], v[122:123]
	s_nop 0
	v_cndmask_b32_e32 v121, 0, v123, vcc
	v_cmp_ge_i32_e32 vcc, v161, v118
	v_add_f32_e32 v123, v125, v166
	v_mul_f32_e32 v123, 0x3fb8aa3b, v123
	v_cndmask_b32_e32 v161, 0, v122, vcc
	v_add_f32_e32 v122, v160, v161
	v_add_f32_e32 v160, v121, v122
	v_add_f32_e32 v122, v125, v167
	v_mul_f32_e32 v122, 0x3fb8aa3b, v122
	v_exp_f32_e32 v122, v122
	v_exp_f32_e32 v123, v123
	v_or_b32_e32 v162, 35, v158
	v_or_b32_e32 v163, 34, v158
	v_cmp_ge_i32_e32 vcc, v162, v118
	v_pk_mul_f32 v[122:123], v[164:165], v[122:123]
	s_nop 0
	v_cndmask_b32_e32 v123, 0, v123, vcc
	v_cmp_ge_i32_e32 vcc, v163, v118
	s_nop 1
	v_cndmask_b32_e32 v162, 0, v122, vcc
	v_add_f32_e32 v122, v162, v160
	v_add_f32_e32 v160, v123, v122
	v_cvt_pk_bf16_f32 v122, v161, v121
	v_cvt_pk_bf16_f32 v123, v162, v123
.LBB0_1364:
	ds_write_b64 v159, v[122:123] offset:64
	s_cmp_gt_i32 s7, 3
	s_cbranch_scc1 .LBB0_1366
	ds_read_b128 v[198:201], v192 offset:47872
	ds_read_b128 v[202:205], v192 offset:47936
	ds_read_b128 v[206:209], v192 offset:48000
	ds_read_b128 v[234:237], v192 offset:48064
	v_or_b32_e32 v168, 48, v158
	v_or_b32_e32 v161, 49, v158
	v_cmp_ge_i32_e32 vcc, v161, v118
	s_waitcnt lgkmcnt(3)
	v_mfma_f32_16x16x32_bf16 v[120:123], v[198:201], v[110:113], 0
	s_waitcnt lgkmcnt(2)
	v_mfma_f32_16x16x32_bf16 v[120:123], v[202:205], v[106:109], v[120:123]
	s_waitcnt lgkmcnt(1)
	v_mfma_f32_16x16x32_bf16 v[120:123], v[206:209], v[102:105], v[120:123]
	s_waitcnt lgkmcnt(0)
	v_mfma_f32_16x16x32_bf16 v[120:123], v[234:237], v[98:101], v[120:123]
	v_lshlrev_b32_e32 v162, 2, v168
	v_sub_u32_e32 v162, 0, v162
	v_add_u32_e32 v162, 0x239f0, v162
	ds_read_b128 v[162:165], v162
	s_waitcnt lgkmcnt(0)
	v_add_f32_e32 v165, v125, v165
	v_add_f32_e32 v164, v125, v164
	v_mul_f32_e32 v165, 0x3fb8aa3b, v165
	v_mul_f32_e32 v164, 0x3fb8aa3b, v164
	v_exp_f32_e32 v166, v165
	v_exp_f32_e32 v167, v164
	v_or_b32_e32 v165, 51, v158
	v_pk_mul_f32 v[120:121], v[120:121], v[166:167]
	s_nop 0
	v_cndmask_b32_e32 v161, 0, v121, vcc
	v_cmp_ge_i32_e32 vcc, v168, v118
	v_add_f32_e32 v121, v125, v162
	v_mul_f32_e32 v121, 0x3fb8aa3b, v121
	v_cndmask_b32_e32 v164, 0, v120, vcc
	v_add_f32_e32 v120, v160, v164
	v_add_f32_e32 v160, v161, v120
	v_add_f32_e32 v120, v125, v163
	v_mul_f32_e32 v120, 0x3fb8aa3b, v120
	v_exp_f32_e32 v120, v120
	v_exp_f32_e32 v121, v121
	v_or_b32_e32 v166, 50, v158
	v_cmp_ge_i32_e32 vcc, v165, v118
	v_pk_mul_f32 v[120:121], v[122:123], v[120:121]
	s_nop 0
	v_cndmask_b32_e32 v121, 0, v121, vcc
	v_cmp_ge_i32_e32 vcc, v166, v118
	s_nop 1
	v_cndmask_b32_e32 v122, 0, v120, vcc
	v_add_f32_e32 v120, v122, v160
	v_add_f32_e32 v160, v121, v120
	v_cvt_pk_bf16_f32 v120, v164, v161
	v_cvt_pk_bf16_f32 v121, v122, v121
	s_branch .LBB0_1367

.LBB0_1367:
	ds_write_b64 v159, v[120:121] offset:96
	v_mov_b32_e32 v120, 0
	s_cmp_gt_i32 s7, 4
	v_mov_b32_e32 v122, 0
	v_mov_b32_e32 v123, 0
	s_cbranch_scc1 .LBB0_1369
	ds_read_b128 v[198:201], v192 offset:52224
	ds_read_b128 v[202:205], v192 offset:52288
	ds_read_b128 v[206:209], v192 offset:52352
	ds_read_b128 v[234:237], v192 offset:52416
	v_or_b32_e32 v161, 64, v158
	v_lshlrev_b32_e32 v122, 2, v161
	v_sub_u32_e32 v122, 0, v122
	v_add_u32_e32 v122, 0x239f0, v122
	v_or_b32_e32 v121, 0x41, v158
	v_cmp_ge_i32_e32 vcc, v121, v118
	s_waitcnt lgkmcnt(3)
	v_mfma_f32_16x16x32_bf16 v[162:165], v[198:201], v[110:113], 0
	s_waitcnt lgkmcnt(2)
	v_mfma_f32_16x16x32_bf16 v[162:165], v[202:205], v[106:109], v[162:165]
	s_waitcnt lgkmcnt(1)
	v_mfma_f32_16x16x32_bf16 v[162:165], v[206:209], v[102:105], v[162:165]
	s_waitcnt lgkmcnt(0)
	v_mfma_f32_16x16x32_bf16 v[162:165], v[234:237], v[98:101], v[162:165]
	ds_read_b128 v[166:169], v122
	s_waitcnt lgkmcnt(0)
	v_add_f32_e32 v122, v125, v169
	v_add_f32_e32 v123, v125, v168
	v_mul_f32_e32 v122, 0x3fb8aa3b, v122
	v_mul_f32_e32 v123, 0x3fb8aa3b, v123
	v_exp_f32_e32 v122, v122
	v_exp_f32_e32 v123, v123
	s_nop 0
	v_pk_mul_f32 v[122:123], v[162:163], v[122:123]
	s_nop 0
	v_cndmask_b32_e32 v121, 0, v123, vcc
	v_cmp_ge_i32_e32 vcc, v161, v118
	v_add_f32_e32 v123, v125, v166
	v_mul_f32_e32 v123, 0x3fb8aa3b, v123
	v_cndmask_b32_e32 v161, 0, v122, vcc
	v_add_f32_e32 v122, v160, v161
	v_add_f32_e32 v160, v121, v122
	v_add_f32_e32 v122, v125, v167
	v_mul_f32_e32 v122, 0x3fb8aa3b, v122
	v_exp_f32_e32 v122, v122
	v_exp_f32_e32 v123, v123
	v_or_b32_e32 v162, 0x43, v158
	v_or_b32_e32 v163, 0x42, v158
	v_cmp_ge_i32_e32 vcc, v162, v118
	v_pk_mul_f32 v[122:123], v[164:165], v[122:123]
	s_nop 0
	v_cndmask_b32_e32 v123, 0, v123, vcc
	v_cmp_ge_i32_e32 vcc, v163, v118
	s_nop 1
	v_cndmask_b32_e32 v162, 0, v122, vcc
	v_add_f32_e32 v122, v162, v160
	v_add_f32_e32 v160, v123, v122
	v_cvt_pk_bf16_f32 v122, v161, v121
	v_cvt_pk_bf16_f32 v123, v162, v123
.LBB0_1369:
	ds_write_b64 v159, v[122:123] offset:128
	s_cmp_gt_i32 s7, 5
	s_cbranch_scc1 .LBB0_1371
	ds_read_b128 v[198:201], v192 offset:56576
	ds_read_b128 v[202:205], v192 offset:56640
	ds_read_b128 v[206:209], v192 offset:56704
	ds_read_b128 v[234:237], v192 offset:56768
	v_or_b32_e32 v168, 0x50, v158
	v_or_b32_e32 v161, 0x51, v158
	v_cmp_ge_i32_e32 vcc, v161, v118
	s_waitcnt lgkmcnt(3)
	v_mfma_f32_16x16x32_bf16 v[120:123], v[198:201], v[110:113], 0
	s_waitcnt lgkmcnt(2)
	v_mfma_f32_16x16x32_bf16 v[120:123], v[202:205], v[106:109], v[120:123]
	s_waitcnt lgkmcnt(1)
	v_mfma_f32_16x16x32_bf16 v[120:123], v[206:209], v[102:105], v[120:123]
	s_waitcnt lgkmcnt(0)
	v_mfma_f32_16x16x32_bf16 v[120:123], v[234:237], v[98:101], v[120:123]
	v_lshlrev_b32_e32 v162, 2, v168
	v_sub_u32_e32 v162, 0, v162
	v_add_u32_e32 v162, 0x239f0, v162
	ds_read_b128 v[162:165], v162
	s_waitcnt lgkmcnt(0)
	v_add_f32_e32 v165, v125, v165
	v_add_f32_e32 v164, v125, v164
	v_mul_f32_e32 v165, 0x3fb8aa3b, v165
	v_mul_f32_e32 v164, 0x3fb8aa3b, v164
	v_exp_f32_e32 v166, v165
	v_exp_f32_e32 v167, v164
	v_or_b32_e32 v165, 0x53, v158
	v_pk_mul_f32 v[120:121], v[120:121], v[166:167]
	s_nop 0
	v_cndmask_b32_e32 v161, 0, v121, vcc
	v_cmp_ge_i32_e32 vcc, v168, v118
	v_add_f32_e32 v121, v125, v162
	v_mul_f32_e32 v121, 0x3fb8aa3b, v121
	v_cndmask_b32_e32 v164, 0, v120, vcc
	v_add_f32_e32 v120, v160, v164
	v_add_f32_e32 v160, v161, v120
	v_add_f32_e32 v120, v125, v163
	v_mul_f32_e32 v120, 0x3fb8aa3b, v120
	v_exp_f32_e32 v120, v120
	v_exp_f32_e32 v121, v121
	v_or_b32_e32 v166, 0x52, v158
	v_cmp_ge_i32_e32 vcc, v165, v118
	v_pk_mul_f32 v[120:121], v[122:123], v[120:121]
	s_nop 0
	v_cndmask_b32_e32 v121, 0, v121, vcc
	v_cmp_ge_i32_e32 vcc, v166, v118
	s_nop 1
	v_cndmask_b32_e32 v122, 0, v120, vcc
	v_add_f32_e32 v120, v122, v160
	v_add_f32_e32 v160, v121, v120
	v_cvt_pk_bf16_f32 v120, v164, v161
	v_cvt_pk_bf16_f32 v121, v122, v121
	s_branch .LBB0_1372

.LBB0_1372:
	ds_write_b64 v159, v[120:121] offset:160
	v_mov_b32_e32 v120, 0
	s_cmp_gt_i32 s7, 6
	v_mov_b32_e32 v122, 0
	v_mov_b32_e32 v123, 0
	s_cbranch_scc1 .LBB0_1374
	ds_read_b128 v[198:201], v192 offset:60928
	ds_read_b128 v[202:205], v192 offset:60992
	ds_read_b128 v[206:209], v192 offset:61056
	ds_read_b128 v[234:237], v192 offset:61120
	v_or_b32_e32 v161, 0x60, v158
	v_lshlrev_b32_e32 v122, 2, v161
	v_sub_u32_e32 v122, 0, v122
	v_add_u32_e32 v122, 0x239f0, v122
	v_or_b32_e32 v121, 0x61, v158
	v_cmp_ge_i32_e32 vcc, v121, v118
	s_waitcnt lgkmcnt(3)
	v_mfma_f32_16x16x32_bf16 v[162:165], v[198:201], v[110:113], 0
	s_waitcnt lgkmcnt(2)
	v_mfma_f32_16x16x32_bf16 v[162:165], v[202:205], v[106:109], v[162:165]
	s_waitcnt lgkmcnt(1)
	v_mfma_f32_16x16x32_bf16 v[162:165], v[206:209], v[102:105], v[162:165]
	s_waitcnt lgkmcnt(0)
	v_mfma_f32_16x16x32_bf16 v[162:165], v[234:237], v[98:101], v[162:165]
	ds_read_b128 v[166:169], v122
	s_waitcnt lgkmcnt(0)
	v_add_f32_e32 v122, v125, v169
	v_add_f32_e32 v123, v125, v168
	v_mul_f32_e32 v122, 0x3fb8aa3b, v122
	v_mul_f32_e32 v123, 0x3fb8aa3b, v123
	v_exp_f32_e32 v122, v122
	v_exp_f32_e32 v123, v123
	s_nop 0
	v_pk_mul_f32 v[122:123], v[162:163], v[122:123]
	s_nop 0
	v_cndmask_b32_e32 v121, 0, v123, vcc
	v_cmp_ge_i32_e32 vcc, v161, v118
	v_add_f32_e32 v123, v125, v166
	v_mul_f32_e32 v123, 0x3fb8aa3b, v123
	v_cndmask_b32_e32 v161, 0, v122, vcc
	v_add_f32_e32 v122, v160, v161
	v_add_f32_e32 v160, v121, v122
	v_add_f32_e32 v122, v125, v167
	v_mul_f32_e32 v122, 0x3fb8aa3b, v122
	v_exp_f32_e32 v122, v122
	v_exp_f32_e32 v123, v123
	v_or_b32_e32 v162, 0x63, v158
	v_or_b32_e32 v163, 0x62, v158
	v_cmp_ge_i32_e32 vcc, v162, v118
	v_pk_mul_f32 v[122:123], v[164:165], v[122:123]
	s_nop 0
	v_cndmask_b32_e32 v123, 0, v123, vcc
	v_cmp_ge_i32_e32 vcc, v163, v118
	s_nop 1
	v_cndmask_b32_e32 v162, 0, v122, vcc
	v_add_f32_e32 v122, v162, v160
	v_add_f32_e32 v160, v123, v122
	v_cvt_pk_bf16_f32 v122, v161, v121
	v_cvt_pk_bf16_f32 v123, v162, v123
.LBB0_1374:
	ds_write_b64 v159, v[122:123] offset:192
	s_cmp_gt_i32 s7, 7
	s_cbranch_scc1 .LBB0_1376
	ds_read_b128 v[198:201], v192 offset:65280
	ds_read_b128 v[202:205], v192 offset:65472
	s_waitcnt lgkmcnt(1)
	v_mfma_f32_16x16x32_bf16 v[110:113], v[198:201], v[110:113], 0
	ds_read_b128 v[120:123], v192 offset:65344
	s_waitcnt lgkmcnt(0)
	v_mfma_f32_16x16x32_bf16 v[106:109], v[120:123], v[106:109], v[110:113]
	s_nop 4
	ds_read_b128 v[110:113], v192 offset:65408
	s_waitcnt lgkmcnt(0)
	v_mfma_f32_16x16x32_bf16 v[102:105], v[110:113], v[102:105], v[106:109]
	s_nop 2
	s_waitcnt lgkmcnt(0)
	v_mfma_f32_16x16x32_bf16 v[98:101], v[202:205], v[98:101], v[102:105]
	v_or_b32_e32 v109, 0x70, v158
	s_nop 1
	v_lshlrev_b32_e32 v102, 2, v109
	v_sub_u32_e32 v102, 0, v102
	v_add_u32_e32 v102, 0x239f0, v102
	ds_read_b128 v[102:105], v102
	v_or_b32_e32 v108, 0x71, v158
	v_cmp_ge_i32_e32 vcc, v108, v118
	v_or_b32_e32 v108, 0x72, v158
	s_waitcnt lgkmcnt(0)
	v_add_f32_e32 v105, v125, v105
	v_add_f32_e32 v104, v125, v104
	v_mul_f32_e32 v105, 0x3fb8aa3b, v105
	v_mul_f32_e32 v104, 0x3fb8aa3b, v104
	v_exp_f32_e32 v106, v105
	v_exp_f32_e32 v107, v104
	s_nop 0
	v_pk_mul_f32 v[98:99], v[98:99], v[106:107]
	s_nop 0
	v_cndmask_b32_e32 v104, 0, v99, vcc
	v_cmp_ge_i32_e32 vcc, v109, v118
	v_add_f32_e32 v99, v125, v102
	v_mul_f32_e32 v99, 0x3fb8aa3b, v99
	v_cndmask_b32_e32 v105, 0, v98, vcc
	v_add_f32_e32 v98, v160, v105
	v_add_f32_e32 v106, v104, v98
	v_add_f32_e32 v98, v125, v103
	v_mul_f32_e32 v98, 0x3fb8aa3b, v98
	v_exp_f32_e32 v98, v98
	v_exp_f32_e32 v99, v99
	v_or_b32_e32 v107, 0x73, v158
	v_cmp_ge_i32_e32 vcc, v107, v118
	v_cvt_pk_bf16_f32 v120, v105, v104
	v_pk_mul_f32 v[98:99], v[100:101], v[98:99]
	s_nop 0
	v_cndmask_b32_e32 v99, 0, v99, vcc
	v_cmp_ge_i32_e32 vcc, v108, v118
	s_nop 1
	v_cndmask_b32_e32 v98, 0, v98, vcc
	v_add_f32_e32 v100, v98, v106
	v_add_f32_e32 v160, v99, v100
	v_cvt_pk_bf16_f32 v121, v98, v99
	s_branch .LBB0_1377

.LBB0_1379:
	s_or_b64 exec, exec, s[4:5]
	v_fmac_f32_e32 v116, v114, v117
	v_max_f32_e32 v98, v115, v115
	v_max_f32_e64 v98, |v116|, v98
	s_waitcnt lgkmcnt(0)
	v_div_scale_f32 v99, s[4:5], v98, v98, 1.0
	v_rcp_f32_e32 v100, v99
	v_pk_fma_f32 v[90:91], v[114:115], v[94:95], v[90:91] op_sel_hi:[0,1,1]
	s_waitcnt lgkmcnt(0)
	s_barrier
	ds_read_b128 v[206:209], v192 offset:64
	ds_read_b128 v[242:245], v192
	ds_read_b128 v[246:249], v192 offset:128
	ds_read_b128 v[250:253], v192 offset:192
	v_fma_f32 v101, -v99, v100, 1.0
	v_fmac_f32_e32 v100, v101, v100
	v_div_scale_f32 v101, vcc, 1.0, v98, 1.0
	v_mul_f32_e32 v102, v101, v100
	v_fma_f32 v103, -v99, v102, v101
	v_fmac_f32_e32 v102, v103, v100
	v_fma_f32 v99, -v99, v102, v101
	v_div_fmas_f32 v99, v99, v100, v102
	v_div_fixup_f32 v98, v99, v98, 1.0
	v_pk_fma_f32 v[102:103], v[90:91], v[98:99], 0 op_sel_hi:[1,0,0]
	v_pk_fma_f32 v[90:91], v[114:115], v[96:97], v[92:93] op_sel_hi:[0,1,1]
	v_pk_fma_f32 v[104:105], v[90:91], v[98:99], 0 op_sel_hi:[1,0,0]
	v_mul_u32_u24_e32 v90, 0x110, v191
	v_add3_u32 v0, s34, v0, v90
	ds_read_b128 v[198:201], v0
	ds_read_b128 v[202:205], v0 offset:64
	ds_read_b128 v[234:237], v0 offset:128
	ds_read_b128 v[238:241], v0 offset:192
	s_waitcnt lgkmcnt(3)
	v_mfma_f32_16x16x32_bf16 v[90:93], v[14:17], v[198:201], 0
	ds_read_b128 v[198:201], v0 offset:4352
	v_xor_b32_e32 v172, 31, v191
	v_lshl_add_u32 v180, v172, 2, s39
	s_waitcnt lgkmcnt(3)
	v_mfma_f32_16x16x32_bf16 v[90:93], v[10:13], v[202:205], v[90:93]
	ds_read_b128 v[202:205], v192 offset:4416
	v_and_b32_e32 v193, 15, v223
	s_waitcnt lgkmcnt(3)
	v_mfma_f32_16x16x32_bf16 v[90:93], v[6:9], v[234:237], v[90:93]
	ds_read_b128 v[234:237], v0 offset:4480
	s_waitcnt lgkmcnt(3)
	v_mfma_f32_16x16x32_bf16 v[90:93], v[2:5], v[238:241], v[90:93]
	ds_read_b128 v[238:241], v0 offset:4544
	s_waitcnt vmcnt(3) lgkmcnt(4)
	v_mfma_f32_16x16x32_bf16 v[94:97], v[86:89], v[242:245], 0
	ds_read_b128 v[242:245], v192 offset:4352
	s_waitcnt vmcnt(2)
	v_mfma_f32_16x16x32_bf16 v[94:97], v[82:85], v[206:209], v[94:97]
	ds_read_b128 v[206:209], v0 offset:4416
	s_waitcnt vmcnt(1) lgkmcnt(6)
	v_mfma_f32_16x16x32_bf16 v[94:97], v[78:81], v[246:249], v[94:97]
	ds_read_b128 v[246:249], v192 offset:4480
	s_waitcnt vmcnt(0) lgkmcnt(7)
	v_mfma_f32_16x16x32_bf16 v[94:97], v[74:77], v[250:253], v[94:97]
	ds_read_b128 v[250:253], v192 offset:4544
	v_xor_b32_e32 v98, 0x7f, v191
	v_lshl_add_u32 v100, v98, 2, s39
	ds_read2st64_b32 v[98:99], v100 offset0:12 offset1:14
	ds_read2st64_b32 v[100:101], v100 offset1:2
	s_waitcnt lgkmcnt(1)
	v_max_f32_e32 v99, v99, v99
	s_waitcnt lgkmcnt(0)
	v_fmac_f32_e32 v100, v98, v101
	v_max_f32_e64 v99, |v100|, v99
	v_div_scale_f32 v100, s[4:5], v99, v99, 1.0
	v_rcp_f32_e32 v101, v100
	v_pk_fma_f32 v[90:91], v[98:99], v[94:95], v[90:91] op_sel_hi:[0,1,1]
	v_cmp_gt_u32_e64 s[4:5], 16, v188
	v_fma_f32 v106, -v100, v101, 1.0
	v_fmac_f32_e32 v101, v106, v101
	v_div_scale_f32 v106, vcc, 1.0, v99, 1.0
	v_mul_f32_e32 v107, v106, v101
	v_fma_f32 v108, -v100, v107, v106
	v_fmac_f32_e32 v107, v108, v101
	v_fma_f32 v100, -v100, v107, v106
	v_div_fmas_f32 v100, v100, v101, v107
	v_div_fixup_f32 v100, v100, v99, 1.0
	v_pk_fma_f32 v[160:161], v[90:91], v[100:101], v[102:103] op_sel_hi:[1,0,1]
	v_pk_fma_f32 v[90:91], v[98:99], v[96:97], v[92:93] op_sel_hi:[0,1,1]
	v_pk_fma_f32 v[158:159], v[90:91], v[100:101], v[104:105] op_sel_hi:[1,0,1]
	s_waitcnt lgkmcnt(0)
	v_mfma_f32_16x16x32_bf16 v[14:17], v[14:17], v[198:201], 0
	ds_read_b128 v[198:201], v0 offset:8768
	s_waitcnt lgkmcnt(1)
	v_mfma_f32_16x16x32_bf16 v[14:17], v[10:13], v[206:209], v[14:17]
	ds_read_b128 v[206:209], v192 offset:8768
	s_waitcnt lgkmcnt(2)
	v_mfma_f32_16x16x32_bf16 v[14:17], v[6:9], v[234:237], v[14:17]
	ds_read_b128 v[234:237], v0 offset:8896
	s_waitcnt lgkmcnt(3)
	v_mfma_f32_16x16x32_bf16 v[14:17], v[2:5], v[238:241], v[14:17]
	ds_read_b128 v[238:241], v192 offset:8704
	s_waitcnt lgkmcnt(4)
	v_mfma_f32_16x16x32_bf16 v[90:93], v[86:89], v[242:245], 0
	ds_read_b128 v[242:245], v192 offset:8832
	v_mfma_f32_16x16x32_bf16 v[90:93], v[82:85], v[202:205], v[90:93]
	ds_read_b128 v[202:205], v0 offset:8832
	s_waitcnt lgkmcnt(6)
	v_mfma_f32_16x16x32_bf16 v[90:93], v[78:81], v[246:249], v[90:93]
	ds_read_b128 v[246:249], v192 offset:8896
	s_waitcnt lgkmcnt(7)
	v_mfma_f32_16x16x32_bf16 v[94:97], v[74:77], v[250:253], v[90:93]
	ds_read_b128 v[250:253], v0 offset:13120
	s_nop 4
	v_xor_b32_e32 v90, 0x6f, v191
	v_lshl_add_u32 v90, v90, 2, s39
	ds_read2st64_b32 v[162:163], v90 offset0:12 offset1:14
	ds_read2st64_b32 v[164:165], v90 offset1:2
	s_waitcnt lgkmcnt(0)
	v_mfma_f32_16x16x32_bf16 v[90:93], v[10:13], v[198:201], 0
	ds_read_b128 v[198:201], v192 offset:13120
	s_waitcnt lgkmcnt(1)
	v_mfma_f32_16x16x32_bf16 v[90:93], v[6:9], v[202:205], v[90:93]
	ds_read_b128 v[202:205], v0 offset:13184
	s_waitcnt lgkmcnt(2)
	v_mfma_f32_16x16x32_bf16 v[90:93], v[2:5], v[234:237], v[90:93]
	ds_read_b128 v[234:237], v192 offset:13056
	s_waitcnt lgkmcnt(3)
	v_mfma_f32_16x16x32_bf16 v[98:101], v[86:89], v[238:241], 0
	ds_read_b128 v[238:241], v192 offset:13184
	v_mfma_f32_16x16x32_bf16 v[98:101], v[82:85], v[206:209], v[98:101]
	ds_read_b128 v[206:209], v0 offset:13248
	s_waitcnt lgkmcnt(5)
	v_mfma_f32_16x16x32_bf16 v[98:101], v[78:81], v[242:245], v[98:101]
	ds_read_b128 v[242:245], v192 offset:13248
	s_waitcnt lgkmcnt(6)
	v_mfma_f32_16x16x32_bf16 v[102:105], v[74:77], v[246:249], v[98:101]
	ds_read_b128 v[246:249], v0 offset:17536
	s_nop 4
	v_xor_b32_e32 v98, 0x5f, v191
	v_lshl_add_u32 v98, v98, 2, s39
	ds_read2st64_b32 v[166:167], v98 offset0:12 offset1:14
	ds_read2st64_b32 v[168:169], v98 offset1:2
	s_waitcnt lgkmcnt(0)
	v_mfma_f32_16x16x32_bf16 v[10:13], v[10:13], v[250:253], 0
	ds_read_b128 v[250:253], v0 offset:17600
	s_waitcnt lgkmcnt(1)
	v_mfma_f32_16x16x32_bf16 v[10:13], v[6:9], v[202:205], v[10:13]
	ds_read_b128 v[202:205], v192 offset:17408
	s_waitcnt lgkmcnt(2)
	v_mfma_f32_16x16x32_bf16 v[10:13], v[2:5], v[206:209], v[10:13]
	ds_read_b128 v[206:209], v192 offset:17536
	s_waitcnt lgkmcnt(3)
	v_mfma_f32_16x16x32_bf16 v[98:101], v[86:89], v[234:237], 0
	ds_read_b128 v[234:237], v192 offset:17600
	v_mfma_f32_16x16x32_bf16 v[98:101], v[82:85], v[198:201], v[98:101]
	ds_read_b128 v[198:201], v192 offset:17472
	s_waitcnt lgkmcnt(5)
	v_mfma_f32_16x16x32_bf16 v[98:101], v[78:81], v[238:241], v[98:101]
	ds_read_b128 v[238:241], v0 offset:21888
	s_waitcnt lgkmcnt(6)
	v_mfma_f32_16x16x32_bf16 v[110:113], v[74:77], v[242:245], v[98:101]
	ds_read_b128 v[242:245], v192 offset:21824
	s_nop 4
	v_xor_b32_e32 v98, 0x4f, v191
	v_lshl_add_u32 v98, v98, 2, s39
	ds_read2st64_b32 v[170:171], v98 offset0:12 offset1:14
	ds_read2st64_b32 v[176:177], v98 offset1:2
	s_waitcnt lgkmcnt(0)
	v_mfma_f32_16x16x32_bf16 v[98:101], v[6:9], v[246:249], 0
	ds_read_b128 v[246:249], v0 offset:21952
	s_waitcnt lgkmcnt(1)
	v_mfma_f32_16x16x32_bf16 v[98:101], v[2:5], v[250:253], v[98:101]
	ds_read_b128 v[250:253], v192 offset:21760
	s_waitcnt lgkmcnt(2)
	v_mfma_f32_16x16x32_bf16 v[106:109], v[86:89], v[202:205], 0
	ds_read_b128 v[202:205], v192 offset:21952
	v_mfma_f32_16x16x32_bf16 v[106:109], v[82:85], v[198:201], v[106:109]
	ds_read_b128 v[198:201], v192 offset:21888
	s_waitcnt lgkmcnt(4)
	v_mfma_f32_16x16x32_bf16 v[106:109], v[78:81], v[206:209], v[106:109]
	ds_read_b128 v[206:209], v0 offset:26304
	s_waitcnt lgkmcnt(5)
	v_mfma_f32_16x16x32_bf16 v[118:121], v[74:77], v[234:237], v[106:109]
	ds_read_b128 v[234:237], v192 offset:26112
	s_nop 4
	v_xor_b32_e32 v106, 63, v191
	v_lshl_add_u32 v106, v106, 2, s39
	ds_read2st64_b32 v[174:175], v106 offset0:12 offset1:14
	ds_read2st64_b32 v[182:183], v106 offset1:2
	s_waitcnt lgkmcnt(0)
	v_mfma_f32_16x16x32_bf16 v[6:9], v[6:9], v[238:241], 0
	ds_read_b128 v[238:241], v192 offset:26176
	s_waitcnt lgkmcnt(1)
	v_mfma_f32_16x16x32_bf16 v[106:109], v[2:5], v[246:249], v[6:9]
	ds_read_b128 v[246:249], v192 offset:26304
	s_nop 4
	s_waitcnt lgkmcnt(2)
	v_mfma_f32_16x16x32_bf16 v[6:9], v[86:89], v[250:253], 0
	ds_read_b128 v[250:253], v0 offset:30656
	v_mfma_f32_16x16x32_bf16 v[6:9], v[82:85], v[242:245], v[6:9]
	ds_read_b128 v[242:245], v192 offset:26240
	s_waitcnt lgkmcnt(4)
	v_mfma_f32_16x16x32_bf16 v[6:9], v[78:81], v[198:201], v[6:9]
	ds_read_b128 v[198:201], v192 offset:30464
	s_waitcnt lgkmcnt(5)
	v_mfma_f32_16x16x32_bf16 v[122:125], v[74:77], v[202:205], v[6:9]
	s_nop 4
	v_xor_b32_e32 v6, 47, v191
	v_lshl_add_u32 v6, v6, 2, s39
	ds_read2st64_b32 v[178:179], v6 offset0:12 offset1:14
	ds_read2st64_b32 v[184:185], v6 offset1:2
	s_waitcnt lgkmcnt(0)
	v_mfma_f32_16x16x32_bf16 v[114:117], v[86:89], v[234:237], 0
	s_waitcnt lgkmcnt(0)
	v_mfma_f32_16x16x32_bf16 v[114:117], v[82:85], v[238:241], v[114:117]
	s_waitcnt lgkmcnt(0)
	v_mfma_f32_16x16x32_bf16 v[114:117], v[78:81], v[242:245], v[114:117]
	ds_read2st64_b32 v[172:173], v180 offset0:12 offset1:14
	ds_read2st64_b32 v[180:181], v180 offset1:2
	s_waitcnt lgkmcnt(2)
	v_mfma_f32_16x16x32_bf16 v[114:117], v[74:77], v[246:249], v[114:117]
	v_xor_b32_e32 v0, 15, v191
	v_lshl_add_u32 v0, v0, 2, s39
	v_mfma_f32_16x16x32_bf16 v[6:9], v[2:5], v[206:209], 0
	s_waitcnt lgkmcnt(0)
	v_mfma_f32_16x16x32_bf16 v[2:5], v[2:5], v[250:253], 0
	s_waitcnt lgkmcnt(0)
	v_mfma_f32_16x16x32_bf16 v[86:89], v[86:89], v[198:201], 0
	ds_read_b128 v[194:197], v192 offset:30528
	s_waitcnt lgkmcnt(0)
	v_mfma_f32_16x16x32_bf16 v[82:85], v[82:85], v[194:197], v[86:89]
	s_nop 4
	ds_read_b128 v[86:89], v192 offset:30592
	s_waitcnt lgkmcnt(0)
	v_mfma_f32_16x16x32_bf16 v[78:81], v[78:81], v[86:89], v[82:85]
	s_nop 2
	ds_read_b128 v[82:85], v192 offset:30656
	v_pk_mul_f32 v[86:87], v[158:159], v[158:159]
	s_waitcnt lgkmcnt(0)
	v_mfma_f32_16x16x32_bf16 v[74:77], v[74:77], v[82:85], v[78:81]
	v_mul_f32_e64 v84, v160, v160
	v_mul_f32_e64 v85, v161, v161
	v_add_f32_e32 v83, v86, v87
	v_add_f32_e32 v84, v84, v85
	v_add_f32_e32 v83, v84, v83
	ds_bpermute_b32 v84, v189, v83
	ds_read2st64_b32 v[78:79], v0 offset0:12 offset1:14
	ds_read2st64_b32 v[80:81], v0 offset1:2
	s_waitcnt lgkmcnt(0)
	s_barrier
	v_lshlrev_b32_e32 v82, 5, v193
	v_add_u32_e32 v0, s45, v82
	s_waitcnt lgkmcnt(2)
	v_add_f32_e32 v83, v83, v84
	ds_bpermute_b32 v84, v190, v83
	v_lshl_add_u32 v0, v186, 2, v0
	s_and_saveexec_b64 s[6:7], s[4:5]
	s_cbranch_execz .LBB0_1381
	s_waitcnt lgkmcnt(0)
	v_add_f32_e32 v83, v83, v84
	ds_write_b32 v0, v83 offset:13824
